# attention: one static s_setprio 1 for the second wave half (w >= 4) for the whole phase, reset at exit; on top of the wave remap
# speedup vs baseline: 1.0060x; 1.0035x over previous
; #define LAS __attribute__((address_space(3)))
; __device__ __forceinline__ void attn_phase(const Params& p, LAS unsigned char* lds, int li, int tid, int G, bf16_t* __restrict__ dst, const bf16_t* __restrict__ ZGA) {
;     ...
;     auto dma_stage = [&](int item, int kb, int buf) {
;         int l = tid & 63; asm volatile("" : "+v"(l));
;         const int tb = item >> 2, hk = item & 3, tk = tb * 128 + (kb - 1) * 128;
;         LAS unsigned char* kl = lds + buf * 65536; LAS unsigned char* vl = kl + 32768;
; #pragma unroll
;         for (int i = 0; i < 4; ++i) {
;             const int r = 4 * (4 * w + i) + (l >> 4), c = (l & 15) ^ (r & 15);
;             __builtin_amdgcn_global_load_lds((const unsigned*)(ZK + (size_t)(tk + r) * 512 + hk * 128 + c * 8), (LAS unsigned*)(kl + (4 * w + i) * 1024), 16, 0, 0);
;             __builtin_amdgcn_global_load_lds((const unsigned*)(ZVT + (size_t)(hk * 128 + r) * T + tk + c * 8), (LAS unsigned*)(vl + (4 * w + i) * 1024), 16, 0, 0);
;         }
;     };
;     int buf = 0, curhk = -1;
;     int ibase, istep, icnt;
;     if (G & 7) { ibase = blockIdx.x; istep = G; icnt = ibase < 1024 ? (1024 - ibase + G - 1) / G : 0; }
;     else { const int nper = G >> 3, j0 = blockIdx.x >> 3; ibase = (blockIdx.x & 7) * 128 + j0; istep = nper; icnt = j0 < 128 ? (128 - j0 + nper - 1) / nper : 0; }
;     u32x4 qraw[3][4];
;     auto load_q = [&](int item, int lq_, int g_) {
;         const int tb = item >> 2, hk = item & 3;
; #pragma unroll
;         for (int mb = 0; mb < 3; ++mb) {
;             const int hh = mb, r = 16 * w + lq_;
;             const bf16_t* qp = Z0 + (size_t)(tb * 128 + r) * 2048 + (3 * hk + hh) * 128 + 8 * g_;
; #pragma unroll
;             for (int ks = 0; ks < 4; ++ks) qraw[mb][ks] = *(const u32x4*)(qp + 32 * ks);
;         }
;     };
;     if (icnt > 0) { dma_stage(ibase, 1, 0); load_q(ibase, tid & 15, (tid & 63) >> 4); }
.LBB0_302:
	s_ashr_i32 s1, s0, 6
	v_writelane_b32 v255, s74, 7
	s_waitcnt lgkmcnt(0)
	s_add_u32 s20, s6, 0xae00000
	s_addc_u32 s21, s7, 0
	v_writelane_b32 v255, s75, 8
	v_writelane_b32 v255, s84, 9
	s_add_u32 s22, s6, 0x12e00000
	s_load_dwordx4 s[8:11], s[4:5], 0x30
	v_writelane_b32 v255, s85, 10
	s_addc_u32 s23, s7, 0
	v_writelane_b32 v255, s86, 11
	s_add_u32 s24, s6, 0x14e00000
	v_writelane_b32 v255, s87, 12
	s_addc_u32 s25, s7, 0
	v_writelane_b32 v255, s78, 13
	s_cmp_gt_i32 s14, 0
	s_mov_b32 s27, 0
	v_writelane_b32 v255, s79, 14
	s_cselect_b64 s[4:5], -1, 0
	s_cmp_lt_i32 s14, 1
	v_and_b32_e32 v200, 63, v0
	v_writelane_b32 v255, s73, 15
	s_cbranch_scc1 .LBB0_304
	v_mov_b32_e32 v1, v200
	s_lshl_b32 s17, s15, 5
	s_waitcnt vmcnt(3)
	v_ashrrev_i32_e32 v6, 4, v1
	s_lshl_b32 s28, s1, 4
	s_bitcmp1_b32 s1, 2
	s_cbranch_scc0 .Laprio0_skip
	s_setprio 1
.Laprio0_skip:
	s_and_b32 s42, s17, 0xffffff80
	v_add_u32_e32 v7, s28, v6
	v_add_u32_e32 v2, s42, v7
	s_lshl_b32 s17, s15, 7
	v_ashrrev_i32_e32 v3, 31, v2
	s_and_b32 s17, s17, 0x180
	v_xor_b32_e32 v4, v6, v1
	v_lshlrev_b64 v[2:3], 10, v[2:3]
	s_lshl_b32 s18, s1, 12
	v_lshl_add_u64 v[2:3], s[22:23], 0, v[2:3]
	s_lshl_b32 s26, s17, 1
	v_lshlrev_b32_e32 v4, 4, v4
	v_lshl_add_u64 v[2:3], v[2:3], 0, s[26:27]
	v_and_b32_e32 v4, 0xf0, v4
	v_mov_b32_e32 v5, 0
	s_add_i32 s29, s18, 0
	v_lshl_add_u64 v[2:3], v[2:3], 0, v[4:5]
	s_mov_b32 m0, s29
	s_ashr_i32 s43, s42, 31
	global_load_lds_dwordx4 v[2:3], off
	v_add_u32_e32 v2, s17, v7
	v_ashrrev_i32_e32 v3, 31, v2
	v_lshlrev_b64 v[2:3], 16, v[2:3]
	v_lshl_add_u64 v[2:3], s[24:25], 0, v[2:3]
	s_lshl_b64 s[18:19], s[42:43], 1
	s_lshl_b32 s34, s1, 2
	v_lshl_add_u64 v[2:3], v[2:3], 0, s[18:19]
	s_or_b32 s35, s34, 1
	v_lshl_add_u64 v[2:3], v[2:3], 0, v[4:5]
	s_add_i32 m0, s29, 0x8000
	v_lshl_add_u32 v7, s35, 2, v6
	global_load_lds_dwordx4 v[2:3], off
	v_add_u32_e32 v2, s42, v7
	v_ashrrev_i32_e32 v3, 31, v2
	v_xor_b32_e32 v4, v7, v1
	v_lshlrev_b64 v[2:3], 10, v[2:3]
	v_lshl_add_u64 v[2:3], s[22:23], 0, v[2:3]
	v_lshlrev_b32_e32 v4, 4, v4
	v_lshl_add_u64 v[2:3], v[2:3], 0, s[26:27]
	v_and_b32_e32 v4, 0xf0, v4
	s_lshl_b32 s35, s35, 10
	v_lshl_add_u64 v[2:3], v[2:3], 0, v[4:5]
	s_add_i32 m0, s35, 0
	s_or_b32 s35, s34, 2
	global_load_lds_dwordx4 v[2:3], off
	v_add_u32_e32 v2, s17, v7
	v_ashrrev_i32_e32 v3, 31, v2
	v_lshlrev_b64 v[2:3], 16, v[2:3]
	v_lshl_add_u64 v[2:3], s[24:25], 0, v[2:3]
	v_lshl_add_u64 v[2:3], v[2:3], 0, s[18:19]
	v_lshl_add_u64 v[2:3], v[2:3], 0, v[4:5]
	s_add_i32 m0, s29, 0x8400
	v_lshl_add_u32 v7, s35, 2, v6
	global_load_lds_dwordx4 v[2:3], off
	v_add_u32_e32 v2, s42, v7
	v_ashrrev_i32_e32 v3, 31, v2
	v_xor_b32_e32 v4, v7, v1
	v_lshlrev_b64 v[2:3], 10, v[2:3]
	v_lshl_add_u64 v[2:3], s[22:23], 0, v[2:3]
	v_lshlrev_b32_e32 v4, 4, v4
	v_lshl_add_u64 v[2:3], v[2:3], 0, s[26:27]
	v_and_b32_e32 v4, 0xf0, v4
	s_lshl_b32 s35, s35, 10
	v_lshl_add_u64 v[2:3], v[2:3], 0, v[4:5]
	s_add_i32 m0, s35, 0
	s_or_b32 s34, s34, 3
	global_load_lds_dwordx4 v[2:3], off
	v_add_u32_e32 v2, s17, v7
	v_ashrrev_i32_e32 v3, 31, v2
	v_lshlrev_b64 v[2:3], 16, v[2:3]
	v_lshl_add_u64 v[2:3], s[24:25], 0, v[2:3]
	v_lshl_add_u64 v[2:3], v[2:3], 0, s[18:19]
	v_lshl_add_u64 v[2:3], v[2:3], 0, v[4:5]
	s_add_i32 m0, s29, 0x8800
	v_lshl_add_u32 v6, s34, 2, v6
	global_load_lds_dwordx4 v[2:3], off
	v_add_u32_e32 v2, s42, v6
	v_ashrrev_i32_e32 v3, 31, v2
	v_xor_b32_e32 v1, v6, v1
	v_lshlrev_b64 v[2:3], 10, v[2:3]
	v_lshl_add_u64 v[2:3], s[22:23], 0, v[2:3]
	v_lshlrev_b32_e32 v1, 4, v1
	v_lshl_add_u64 v[2:3], v[2:3], 0, s[26:27]
	v_and_b32_e32 v4, 0xf0, v1
	s_lshl_b32 s26, s34, 10
	v_lshl_add_u64 v[2:3], v[2:3], 0, v[4:5]
	s_add_i32 m0, s26, 0
	v_and_or_b32 v1, v0, 15, s28
	global_load_lds_dwordx4 v[2:3], off
	v_add_u32_e32 v2, s17, v6
	v_ashrrev_i32_e32 v3, 31, v2
	v_lshlrev_b64 v[2:3], 16, v[2:3]
	v_lshl_add_u64 v[2:3], s[24:25], 0, v[2:3]
	v_lshl_add_u64 v[2:3], v[2:3], 0, s[18:19]
	v_lshl_add_u64 v[2:3], v[2:3], 0, v[4:5]
	s_add_i32 m0, s29, 0x8c00
	s_and_b32 s17, s15, 3
	global_load_lds_dwordx4 v[2:3], off
	v_add_u32_e32 v2, s42, v1
	v_ashrrev_i32_e32 v3, 31, v2
	v_lshlrev_b64 v[2:3], 12, v[2:3]
	v_lshl_add_u64 v[2:3], s[20:21], 0, v[2:3]
	s_mul_i32 s26, s17, 0x300
	v_lshl_add_u64 v[2:3], v[2:3], 0, s[26:27]
	v_and_b32_e32 v4, 48, v0
	v_lshl_add_u64 v[0:1], v[2:3], 0, v[4:5]
	global_load_dwordx4 v[136:139], v[0:1], off
	global_load_dwordx4 v[106:109], v[0:1], off offset:64
	global_load_dwordx4 v[102:105], v[0:1], off offset:128
	global_load_dwordx4 v[98:101], v[0:1], off offset:192
	global_load_dwordx4 v[124:127], v[0:1], off offset:256
	global_load_dwordx4 v[120:123], v[0:1], off offset:320
	global_load_dwordx4 v[116:119], v[0:1], off offset:384
	global_load_dwordx4 v[112:115], v[0:1], off offset:448
	global_load_dwordx4 v[132:135], v[0:1], off offset:512
	global_load_dwordx4 v[128:131], v[0:1], off offset:576
	global_load_dwordx4 v[144:147], v[0:1], off offset:640
	global_load_dwordx4 v[140:143], v[0:1], off offset:704
	s_branch .LBB0_305

; __device__ __forceinline__ unsigned xb_add(unsigned* p, unsigned v) { return __hip_atomic_fetch_add(p, v, __ATOMIC_RELAXED, __HIP_MEMORY_SCOPE_AGENT); }
; __device__ __forceinline__ void attn_phase(const Params& p, LAS unsigned char* lds, int li, int tid, int G, bf16_t* __restrict__ dst, const bf16_t* __restrict__ ZGA) {
;     ...
;     asm volatile("s_waitcnt vmcnt(0)" ::: "memory");
;     __syncthreads();
; __device__ __forceinline__ void xcd_barrier(const XcdBarrier& b) {
;     asm volatile("s_waitcnt vmcnt(0)" ::: "memory");
;     __syncthreads();
;     if (threadIdx.x == 0) {
;         unsigned* bar = b.bar;
;         __builtin_amdgcn_s_waitcnt(0);
;         const unsigned nloc = b.nloc, nx = b.nx;
;         const unsigned old = xb_add(&bar[XB_XSUB(b.x)], 1u);
.LBB0_368:
	s_setprio 0
	s_waitcnt vmcnt(0)
	s_waitcnt vmcnt(0) lgkmcnt(0)
	s_barrier
	s_waitcnt vmcnt(0)
	s_barrier
	s_and_saveexec_b64 s[4:5], s[96:97]
	v_readlane_b32 s92, v255, 7
	v_readlane_b32 s88, v255, 9
	v_readlane_b32 s94, v255, 13
	v_readlane_b32 s93, v255, 8
	v_readlane_b32 s90, v255, 11
	v_readlane_b32 s91, v255, 12
	v_readlane_b32 s95, v255, 14
	v_readlane_b32 s83, v255, 15
	v_readlane_b32 s89, v255, 10
	s_cbranch_execz .LBB0_405
	s_mov_b64 s[8:9], exec
	s_lshl_b32 s0, s83, 8
	v_mbcnt_lo_u32_b32 v0, s8, 0
	s_add_u32 s6, s94, s0
	v_mbcnt_hi_u32_b32 v0, s9, v0
	s_addc_u32 s7, s95, 0
	v_cmp_eq_u32_e32 vcc, 0, v0
	s_waitcnt vmcnt(0) expcnt(0) lgkmcnt(0)
	s_and_saveexec_b64 s[10:11], vcc
	s_cbranch_execz .LBB0_371
	s_bcnt1_i32_b64 s0, s[8:9]
	v_mov_b32_e32 v1, 0x1000
	v_mov_b32_e32 v2, s0
	global_atomic_add v1, v1, v2, s[6:7] offset:1024 sc0

; #define LAS __attribute__((address_space(3)))
; __device__ __forceinline__ void attn_phase(const Params& p, LAS unsigned char* lds, int li, int tid, int G, bf16_t* __restrict__ dst, const bf16_t* __restrict__ ZGA) {
;     ...
;     auto dma_stage = [&](int item, int kb, int buf) {
;         int l = tid & 63; asm volatile("" : "+v"(l));
;         const int tb = item >> 2, hk = item & 3, tk = tb * 128 + (kb - 1) * 128;
;         LAS unsigned char* kl = lds + buf * 65536; LAS unsigned char* vl = kl + 32768;
; #pragma unroll
;         for (int i = 0; i < 4; ++i) {
;             const int r = 4 * (4 * w + i) + (l >> 4), c = (l & 15) ^ (r & 15);
;             __builtin_amdgcn_global_load_lds((const unsigned*)(ZK + (size_t)(tk + r) * 512 + hk * 128 + c * 8), (LAS unsigned*)(kl + (4 * w + i) * 1024), 16, 0, 0);
;             __builtin_amdgcn_global_load_lds((const unsigned*)(ZVT + (size_t)(hk * 128 + r) * T + tk + c * 8), (LAS unsigned*)(vl + (4 * w + i) * 1024), 16, 0, 0);
;         }
;     };
;     int buf = 0, curhk = -1;
;     int ibase, istep, icnt;
;     if (G & 7) { ibase = blockIdx.x; istep = G; icnt = ibase < 1024 ? (1024 - ibase + G - 1) / G : 0; }
;     else { const int nper = G >> 3, j0 = blockIdx.x >> 3; ibase = (blockIdx.x & 7) * 128 + j0; istep = nper; icnt = j0 < 128 ? (128 - j0 + nper - 1) / nper : 0; }
;     u32x4 qraw[3][4];
;     auto load_q = [&](int item, int lq_, int g_) {
;         const int tb = item >> 2, hk = item & 3;
; #pragma unroll
;         for (int mb = 0; mb < 3; ++mb) {
;             const int hh = mb, r = 16 * w + lq_;
;             const bf16_t* qp = Z0 + (size_t)(tb * 128 + r) * 2048 + (3 * hk + hh) * 128 + 8 * g_;
; #pragma unroll
;             for (int ks = 0; ks < 4; ++ks) qraw[mb][ks] = *(const u32x4*)(qp + 32 * ks);
;         }
;     };
;     if (icnt > 0) { dma_stage(ibase, 1, 0); load_q(ibase, tid & 15, (tid & 63) >> 4); }
.LBB0_1056:
	s_ashr_i32 s1, s0, 6
	s_waitcnt lgkmcnt(0)
	s_add_u32 s12, s10, 0xae00000
	s_addc_u32 s13, s11, 0
	s_add_u32 s50, s10, 0x12e00000
	s_load_dwordx4 s[16:19], s[8:9], 0x30
	s_addc_u32 s51, s11, 0
	s_add_u32 s52, s10, 0x14e00000
	s_addc_u32 s53, s11, 0
	s_cmp_gt_i32 s21, 0
	s_mov_b32 s29, 0
	s_cselect_b64 s[8:9], -1, 0
	s_cmp_lt_i32 s21, 1
	v_and_b32_e32 v200, 63, v0
	s_cbranch_scc1 .LBB0_1058
	v_mov_b32_e32 v1, v200
	s_lshl_b32 s4, s2, 5
	s_waitcnt vmcnt(3)
	v_ashrrev_i32_e32 v6, 4, v1
	s_lshl_b32 s7, s1, 4
	s_bitcmp1_b32 s1, 2
	s_cbranch_scc0 .Laprio1_skip
	s_setprio 1
.Laprio1_skip:
	s_and_b32 s54, s4, 0xffffff80
	v_add_u32_e32 v7, s7, v6
	v_add_u32_e32 v2, s54, v7
	s_lshl_b32 s4, s2, 7
	v_ashrrev_i32_e32 v3, 31, v2
	s_and_b32 s6, s4, 0x180
	v_xor_b32_e32 v4, v6, v1
	v_lshlrev_b64 v[2:3], 10, v[2:3]
	s_lshl_b32 s4, s1, 12
	v_lshl_add_u64 v[2:3], s[50:51], 0, v[2:3]
	s_lshl_b32 s28, s6, 1
	v_lshlrev_b32_e32 v4, 4, v4
	v_lshl_add_u64 v[2:3], v[2:3], 0, s[28:29]
	v_and_b32_e32 v4, 0xf0, v4
	v_mov_b32_e32 v5, 0
	s_add_i32 s14, s4, 0
	v_lshl_add_u64 v[2:3], v[2:3], 0, v[4:5]
	s_mov_b32 m0, s14
	s_ashr_i32 s55, s54, 31
	global_load_lds_dwordx4 v[2:3], off
	v_add_u32_e32 v2, s6, v7
	v_ashrrev_i32_e32 v3, 31, v2
	v_lshlrev_b64 v[2:3], 16, v[2:3]
	v_lshl_add_u64 v[2:3], s[52:53], 0, v[2:3]
	s_lshl_b64 s[4:5], s[54:55], 1
	s_lshl_b32 s15, s1, 2
	v_lshl_add_u64 v[2:3], v[2:3], 0, s[4:5]
	s_or_b32 s23, s15, 1
	v_lshl_add_u64 v[2:3], v[2:3], 0, v[4:5]
	s_add_i32 m0, s14, 0x8000
	v_lshl_add_u32 v7, s23, 2, v6
	global_load_lds_dwordx4 v[2:3], off
	v_add_u32_e32 v2, s54, v7
	v_ashrrev_i32_e32 v3, 31, v2
	v_xor_b32_e32 v4, v7, v1
	v_lshlrev_b64 v[2:3], 10, v[2:3]
	v_lshl_add_u64 v[2:3], s[50:51], 0, v[2:3]
	v_lshlrev_b32_e32 v4, 4, v4
	v_lshl_add_u64 v[2:3], v[2:3], 0, s[28:29]
	v_and_b32_e32 v4, 0xf0, v4
	s_lshl_b32 s23, s23, 10
	v_lshl_add_u64 v[2:3], v[2:3], 0, v[4:5]
	s_add_i32 m0, s23, 0
	s_or_b32 s23, s15, 2
	global_load_lds_dwordx4 v[2:3], off
	v_add_u32_e32 v2, s6, v7
	v_ashrrev_i32_e32 v3, 31, v2
	v_lshlrev_b64 v[2:3], 16, v[2:3]
	v_lshl_add_u64 v[2:3], s[52:53], 0, v[2:3]
	v_lshl_add_u64 v[2:3], v[2:3], 0, s[4:5]
	v_lshl_add_u64 v[2:3], v[2:3], 0, v[4:5]
	s_add_i32 m0, s14, 0x8400
	v_lshl_add_u32 v7, s23, 2, v6
	global_load_lds_dwordx4 v[2:3], off
	v_add_u32_e32 v2, s54, v7
	v_ashrrev_i32_e32 v3, 31, v2
	v_xor_b32_e32 v4, v7, v1
	v_lshlrev_b64 v[2:3], 10, v[2:3]
	v_lshl_add_u64 v[2:3], s[50:51], 0, v[2:3]
	v_lshlrev_b32_e32 v4, 4, v4
	v_lshl_add_u64 v[2:3], v[2:3], 0, s[28:29]
	v_and_b32_e32 v4, 0xf0, v4
	s_lshl_b32 s23, s23, 10
	v_lshl_add_u64 v[2:3], v[2:3], 0, v[4:5]
	s_add_i32 m0, s23, 0
	s_or_b32 s15, s15, 3
	global_load_lds_dwordx4 v[2:3], off
	v_add_u32_e32 v2, s6, v7
	v_ashrrev_i32_e32 v3, 31, v2
	v_lshlrev_b64 v[2:3], 16, v[2:3]
	v_lshl_add_u64 v[2:3], s[52:53], 0, v[2:3]
	v_lshl_add_u64 v[2:3], v[2:3], 0, s[4:5]
	v_lshl_add_u64 v[2:3], v[2:3], 0, v[4:5]
	s_add_i32 m0, s14, 0x8800
	v_lshl_add_u32 v6, s15, 2, v6
	global_load_lds_dwordx4 v[2:3], off
	v_add_u32_e32 v2, s54, v6
	v_ashrrev_i32_e32 v3, 31, v2
	v_xor_b32_e32 v1, v6, v1
	v_lshlrev_b64 v[2:3], 10, v[2:3]
	v_lshl_add_u64 v[2:3], s[50:51], 0, v[2:3]
	v_lshlrev_b32_e32 v1, 4, v1
	v_lshl_add_u64 v[2:3], v[2:3], 0, s[28:29]
	v_and_b32_e32 v4, 0xf0, v1
	s_lshl_b32 s15, s15, 10
	v_lshl_add_u64 v[2:3], v[2:3], 0, v[4:5]
	s_add_i32 m0, s15, 0
	v_and_or_b32 v1, v0, 15, s7
	global_load_lds_dwordx4 v[2:3], off
	v_add_u32_e32 v2, s6, v6
	v_ashrrev_i32_e32 v3, 31, v2
	v_lshlrev_b64 v[2:3], 16, v[2:3]
	v_lshl_add_u64 v[2:3], s[52:53], 0, v[2:3]
	v_lshl_add_u64 v[2:3], v[2:3], 0, s[4:5]
	v_lshl_add_u64 v[2:3], v[2:3], 0, v[4:5]
	s_add_i32 m0, s14, 0x8c00
	s_and_b32 s4, s2, 3
	global_load_lds_dwordx4 v[2:3], off
	v_add_u32_e32 v2, s54, v1
	v_ashrrev_i32_e32 v3, 31, v2
	v_lshlrev_b64 v[2:3], 12, v[2:3]
	v_lshl_add_u64 v[2:3], s[12:13], 0, v[2:3]
	s_mul_i32 s28, s4, 0x300
	v_lshl_add_u64 v[2:3], v[2:3], 0, s[28:29]
	v_and_b32_e32 v4, 48, v0
	v_lshl_add_u64 v[0:1], v[2:3], 0, v[4:5]
	global_load_dwordx4 v[110:113], v[0:1], off
	global_load_dwordx4 v[106:109], v[0:1], off offset:64
	global_load_dwordx4 v[102:105], v[0:1], off offset:128
	global_load_dwordx4 v[98:101], v[0:1], off offset:192
	global_load_dwordx4 v[134:137], v[0:1], off offset:256
	global_load_dwordx4 v[130:133], v[0:1], off offset:320
	global_load_dwordx4 v[126:129], v[0:1], off offset:384
	global_load_dwordx4 v[122:125], v[0:1], off offset:448
	global_load_dwordx4 v[118:121], v[0:1], off offset:512
	global_load_dwordx4 v[114:117], v[0:1], off offset:576
	global_load_dwordx4 v[142:145], v[0:1], off offset:640
	global_load_dwordx4 v[138:141], v[0:1], off offset:704
	s_add_u32 s28, s48, 0xae00000
	s_addc_u32 s29, s49, 0
	s_andn2_b64 vcc, exec, s[8:9]
	s_cbranch_vccz .LBB0_1059
	s_branch .LBB0_1121

; __device__ __forceinline__ unsigned xb_add(unsigned* p, unsigned v) { return __hip_atomic_fetch_add(p, v, __ATOMIC_RELAXED, __HIP_MEMORY_SCOPE_AGENT); }
; __device__ __forceinline__ void attn_phase(const Params& p, LAS unsigned char* lds, int li, int tid, int G, bf16_t* __restrict__ dst, const bf16_t* __restrict__ ZGA) {
;     ...
;     asm volatile("s_waitcnt vmcnt(0)" ::: "memory");
;     __syncthreads();
; __device__ __forceinline__ void xcd_barrier(const XcdBarrier& b) {
;     asm volatile("s_waitcnt vmcnt(0)" ::: "memory");
;     __syncthreads();
;     if (threadIdx.x == 0) {
;         unsigned* bar = b.bar;
;         __builtin_amdgcn_s_waitcnt(0);
;         const unsigned nloc = b.nloc, nx = b.nx;
;         const unsigned old = xb_add(&bar[XB_XSUB(b.x)], 1u);
.LBB0_1121:
	s_setprio 0
	s_waitcnt vmcnt(0)
	s_waitcnt vmcnt(0) lgkmcnt(0)
	s_barrier
	s_waitcnt vmcnt(0)
	s_barrier
	s_and_saveexec_b64 s[8:9], s[96:97]
	v_readlane_b32 s88, v255, 9
	v_readlane_b32 s89, v255, 10
	v_readlane_b32 s82, v255, 7
	v_readlane_b32 s88, v255, 13
	v_readlane_b32 s83, v255, 8
	v_readlane_b32 s90, v255, 11
	v_readlane_b32 s91, v255, 12
	v_readlane_b32 s89, v255, 14
	v_readlane_b32 s84, v255, 15
	s_cbranch_execz .LBB0_1158
	s_mov_b64 s[12:13], exec
	s_lshl_b32 s0, s84, 8
	v_mbcnt_lo_u32_b32 v0, s12, 0
	s_add_u32 s10, s88, s0
	v_mbcnt_hi_u32_b32 v0, s13, v0
	s_addc_u32 s11, s89, 0
	v_cmp_eq_u32_e32 vcc, 0, v0
	s_waitcnt vmcnt(0) expcnt(0) lgkmcnt(0)
	s_and_saveexec_b64 s[16:17], vcc
	s_cbranch_execz .LBB0_1124
	s_bcnt1_i32_b64 s0, s[12:13]
	v_mov_b32_e32 v1, 0x1000
	v_mov_b32_e32 v2, s0
	global_atomic_add v1, v1, v2, s[10:11] offset:1024 sc0
